# P6/P9 GEMM residual epilogues rewritten as 6-deep software-pipelined load/fma/store (bit-identical math)
# speedup vs baseline: 1.0125x; 1.0125x over previous
; template <class Epi>
; __device__ __forceinline__ void gemm_phase(unsigned char* lds_g, const bf16_t* A0, const bf16_t* A1, int lda, const bf16_t* Bt, int K,
;                            int mtiles, int ntiles, int ksplit, Epi epi) {
;     ...
; #pragma unroll
;       for (int ai = 0; ai < 2; ++ai)
; #pragma unroll
;         for (int bj = 0; bj < 2; ++bj)
; #pragma unroll
;           for (int m = 0; m < 4; ++m)
;             epi(cur.brow + ai * HALF + wr * 64 + m * 16 + fr, cur.bcol + bj * HALF + wc * 32 + fq * 8, acc[ai][bj][m][0], acc[ai][bj][m][1], cur.piece);
; __global__ void __launch_bounds__(512) fwd_kernel(Params p) {
;     ...
;                  [=](int m, int n, f32x4 v, f32x4 w, int) {
;                    const float* src; float* dst; const float* g;
;                    if (m < NLAT) { src = xin + (size_t)m * 1024 + n; dst = p.out + (size_t)m * 1024 + n; g = modl + (size_t)(m >> 11) * 6144 + 2 * 1024 + n; }
;                    else { src = cres + (size_t)(m - NLAT) * 1024 + n; dst = ctxs + (size_t)(m - NLAT) * 1024 + n; g = modl + (size_t)8 * 6144 + 2 * 1024 + n; }
;                    const float4 s4 = *(const float4*)src; const float4 g4 = *(const float4*)g;
;                    const float4 s5 = *(const float4*)(src + 4); const float4 g5 = *(const float4*)(g + 4);
;                    float4 o; o.x = s4.x + g4.x * v[0]; o.y = s4.y + g4.y * v[1]; o.z = s4.z + g4.z * v[2]; o.w = s4.w + g4.w * v[3];
;                    float4 o2; o2.x = s5.x + g5.x * w[0]; o2.y = s5.y + g5.y * w[1]; o2.z = s5.z + g5.z * w[2]; o2.w = s5.w + g5.w * w[3];
;                    *(float4*)dst = o; *(float4*)(dst + 4) = o2;
.LBB0_893:
	s_cmpk_lt_i32 s33, 0x4000
	s_cbranch_scc0 .Lp6e_ctx
	v_readlane_b32 s2, v253, 55
	v_readlane_b32 s3, v253, 56
	s_mov_b64 s[4:5], s[86:87]
	s_lshr_b32 s1, s33, 11
	s_mul_i32 s1, s1, 0x6000
	s_add_u32 s22, s10, s1
	s_addc_u32 s23, s11, 0
	s_add_u32 s22, s22, 0x2000
	s_addc_u32 s23, s23, 0
	s_mov_b32 s1, s33
	s_branch .Lp6e_join
.Lp6e_ctx:
	v_readlane_b32 s2, v253, 57
	v_readlane_b32 s3, v253, 58
	v_readlane_b32 s4, v250, 59
	v_readlane_b32 s5, v250, 60
	s_mov_b64 s[22:23], s[12:13]
	s_add_i32 s1, s33, 0xffffc000
.Lp6e_join:
	s_nop 3
	s_lshl_b32 s38, s0, 2
	s_lshl_b32 s1, s1, 12
	s_add_u32 s1, s1, s38
	s_add_u32 s2, s2, s1
	s_addc_u32 s3, s3, 0
	s_add_u32 s4, s4, s1
	s_addc_u32 s5, s5, 0
	s_add_u32 s22, s22, s38
	s_addc_u32 s23, s23, 0
	v_lshlrev_b32_e32 v157, 2, v164
	v_lshl_add_u32 v156, v162, 12, v157
	global_load_dwordx4 v[140:143], v157, s[22:23]
	global_load_dwordx4 v[144:147], v157, s[22:23] offset:16
	global_load_dwordx4 v[148:151], v157, s[22:23] offset:512
	global_load_dwordx4 v[152:155], v157, s[22:23] offset:528
	global_load_dwordx4 v[166:169], v156, s[2:3]
	global_load_dwordx4 v[170:173], v156, s[2:3] offset:16
	v_add_u32_e32 v157, 0x10000, v156
	global_load_dwordx4 v[174:177], v157, s[2:3]
	global_load_dwordx4 v[178:181], v157, s[2:3] offset:16
	v_add_u32_e32 v157, 0x20000, v156
	global_load_dwordx4 v[182:185], v157, s[2:3]
	global_load_dwordx4 v[186:189], v157, s[2:3] offset:16
	v_add_u32_e32 v157, 0x30000, v156
	global_load_dwordx4 v[198:201], v157, s[2:3]
	global_load_dwordx4 v[202:205], v157, s[2:3] offset:16
	global_load_dwordx4 v[206:209], v156, s[2:3] offset:512
	global_load_dwordx4 v[210:213], v156, s[2:3] offset:528
	v_add_u32_e32 v157, 0x10000, v156
	global_load_dwordx4 v[214:217], v157, s[2:3] offset:512
	global_load_dwordx4 v[218:221], v157, s[2:3] offset:528
	s_waitcnt vmcnt(10)
	v_pk_fma_f32 v[124:125], v[124:125], v[140:141], v[166:167]
	v_pk_fma_f32 v[126:127], v[126:127], v[142:143], v[168:169]
	v_pk_fma_f32 v[120:121], v[120:121], v[144:145], v[170:171]
	v_pk_fma_f32 v[122:123], v[122:123], v[146:147], v[172:173]
	global_store_dwordx4 v156, v[124:127], s[4:5]
	global_store_dwordx4 v156, v[120:123], s[4:5] offset:16
	v_add_u32_e32 v157, 0x20000, v156
	global_load_dwordx4 v[166:169], v157, s[2:3] offset:512
	global_load_dwordx4 v[170:173], v157, s[2:3] offset:528
	s_waitcnt vmcnt(12)
	v_pk_fma_f32 v[116:117], v[116:117], v[140:141], v[174:175]
	v_pk_fma_f32 v[118:119], v[118:119], v[142:143], v[176:177]
	v_pk_fma_f32 v[112:113], v[112:113], v[144:145], v[178:179]
	v_pk_fma_f32 v[114:115], v[114:115], v[146:147], v[180:181]
	v_add_u32_e32 v190, 0x10000, v156
	global_store_dwordx4 v190, v[116:119], s[4:5]
	global_store_dwordx4 v190, v[112:115], s[4:5] offset:16
	v_add_u32_e32 v157, 0x30000, v156
	global_load_dwordx4 v[174:177], v157, s[2:3] offset:512
	global_load_dwordx4 v[178:181], v157, s[2:3] offset:528
	s_waitcnt vmcnt(14)
	v_pk_fma_f32 v[108:109], v[108:109], v[140:141], v[182:183]
	v_pk_fma_f32 v[110:111], v[110:111], v[142:143], v[184:185]
	v_pk_fma_f32 v[104:105], v[104:105], v[144:145], v[186:187]
	v_pk_fma_f32 v[106:107], v[106:107], v[146:147], v[188:189]
	v_add_u32_e32 v190, 0x20000, v156
	global_store_dwordx4 v190, v[108:111], s[4:5]
	global_store_dwordx4 v190, v[104:107], s[4:5] offset:16
	v_add_u32_e32 v157, 0x80000, v156
	global_load_dwordx4 v[182:185], v157, s[2:3]
	global_load_dwordx4 v[186:189], v157, s[2:3] offset:16
	s_waitcnt vmcnt(16)
	v_pk_fma_f32 v[100:101], v[100:101], v[140:141], v[198:199]
	v_pk_fma_f32 v[102:103], v[102:103], v[142:143], v[200:201]
	v_pk_fma_f32 v[96:97], v[96:97], v[144:145], v[202:203]
	v_pk_fma_f32 v[98:99], v[98:99], v[146:147], v[204:205]
	v_add_u32_e32 v190, 0x30000, v156
	global_store_dwordx4 v190, v[100:103], s[4:5]
	global_store_dwordx4 v190, v[96:99], s[4:5] offset:16
	v_add_u32_e32 v157, 0x90000, v156
	global_load_dwordx4 v[198:201], v157, s[2:3]
	global_load_dwordx4 v[202:205], v157, s[2:3] offset:16
	s_waitcnt vmcnt(18)
	v_pk_fma_f32 v[92:93], v[92:93], v[148:149], v[206:207]
	v_pk_fma_f32 v[94:95], v[94:95], v[150:151], v[208:209]
	v_pk_fma_f32 v[88:89], v[88:89], v[152:153], v[210:211]
	v_pk_fma_f32 v[90:91], v[90:91], v[154:155], v[212:213]
	global_store_dwordx4 v156, v[92:95], s[4:5] offset:512
	global_store_dwordx4 v156, v[88:91], s[4:5] offset:528
	v_add_u32_e32 v157, 0xa0000, v156
	global_load_dwordx4 v[206:209], v157, s[2:3]
	global_load_dwordx4 v[210:213], v157, s[2:3] offset:16
	s_waitcnt vmcnt(20)
	v_pk_fma_f32 v[84:85], v[84:85], v[148:149], v[214:215]
	v_pk_fma_f32 v[86:87], v[86:87], v[150:151], v[216:217]
	v_pk_fma_f32 v[80:81], v[80:81], v[152:153], v[218:219]
	v_pk_fma_f32 v[82:83], v[82:83], v[154:155], v[220:221]
	v_add_u32_e32 v190, 0x10000, v156
	global_store_dwordx4 v190, v[84:87], s[4:5] offset:512
	global_store_dwordx4 v190, v[80:83], s[4:5] offset:528
	v_add_u32_e32 v157, 0xb0000, v156
	global_load_dwordx4 v[214:217], v157, s[2:3]
	global_load_dwordx4 v[218:221], v157, s[2:3] offset:16
	s_waitcnt vmcnt(20)
; #define PG8_BAR __builtin_amdgcn_s_barrier()
; template <class Epi>
; __device__ __forceinline__ void gemm_phase(unsigned char* lds_g, const bf16_t* A0, const bf16_t* A1, int lda, const bf16_t* Bt, int K,
;                            int mtiles, int ntiles, int ksplit, Epi epi) {
;     ...
;       if (!has_next) break;
; #pragma unroll
;       for (int a = 0; a < 2; ++a)
; #pragma unroll
;         for (int b = 0; b < 2; ++b)
; #pragma unroll
;           for (int m = 0; m < 4; ++m)
; #pragma unroll
;             for (int n = 0; n < 2; ++n) acc[a][b][m][n] = (f32x4){0.f, 0.f, 0.f, 0.f};
;       cur = nxt; cA = nA; cB = nB; ++ui;
;       if (G_ALIGN) { if (wr == 1) PG8_BAR; }
; __global__ void __launch_bounds__(512) fwd_kernel(Params p) {
;     ...
;                  [=](int m, int n, f32x4 v, f32x4 w, int) {
;                    const float* src; float* dst; const float* g;
;                    if (m < NLAT) { src = xin + (size_t)m * 1024 + n; dst = p.out + (size_t)m * 1024 + n; g = modl + (size_t)(m >> 11) * 6144 + 2 * 1024 + n; }
;                    else { src = cres + (size_t)(m - NLAT) * 1024 + n; dst = ctxs + (size_t)(m - NLAT) * 1024 + n; g = modl + (size_t)8 * 6144 + 2 * 1024 + n; }
;                    const float4 s4 = *(const float4*)src; const float4 g4 = *(const float4*)g;
;                    const float4 s5 = *(const float4*)(src + 4); const float4 g5 = *(const float4*)(g + 4);
;                    float4 o; o.x = s4.x + g4.x * v[0]; o.y = s4.y + g4.y * v[1]; o.z = s4.z + g4.z * v[2]; o.w = s4.w + g4.w * v[3];
;                    float4 o2; o2.x = s5.x + g5.x * w[0]; o2.y = s5.y + g5.y * w[1]; o2.z = s5.z + g5.z * w[2]; o2.w = s5.w + g5.w * w[3];
;                    *(float4*)dst = o; *(float4*)(dst + 4) = o2;
	v_pk_fma_f32 v[76:77], v[76:77], v[148:149], v[166:167]
	v_pk_fma_f32 v[78:79], v[78:79], v[150:151], v[168:169]
	v_pk_fma_f32 v[72:73], v[72:73], v[152:153], v[170:171]
	v_pk_fma_f32 v[74:75], v[74:75], v[154:155], v[172:173]
	v_add_u32_e32 v190, 0x20000, v156
	global_store_dwordx4 v190, v[76:79], s[4:5] offset:512
	global_store_dwordx4 v190, v[72:75], s[4:5] offset:528
	v_add_u32_e32 v157, 0x80000, v156
	global_load_dwordx4 v[166:169], v157, s[2:3] offset:512
	global_load_dwordx4 v[170:173], v157, s[2:3] offset:528
	s_waitcnt vmcnt(20)
	v_pk_fma_f32 v[68:69], v[68:69], v[148:149], v[174:175]
	v_pk_fma_f32 v[70:71], v[70:71], v[150:151], v[176:177]
	v_pk_fma_f32 v[64:65], v[64:65], v[152:153], v[178:179]
	v_pk_fma_f32 v[66:67], v[66:67], v[154:155], v[180:181]
	v_add_u32_e32 v190, 0x30000, v156
	global_store_dwordx4 v190, v[68:71], s[4:5] offset:512
	global_store_dwordx4 v190, v[64:67], s[4:5] offset:528
	v_add_u32_e32 v157, 0x90000, v156
	global_load_dwordx4 v[174:177], v157, s[2:3] offset:512
	global_load_dwordx4 v[178:181], v157, s[2:3] offset:528
	s_waitcnt vmcnt(20)
	v_pk_fma_f32 v[60:61], v[60:61], v[140:141], v[182:183]
	v_pk_fma_f32 v[62:63], v[62:63], v[142:143], v[184:185]
	v_pk_fma_f32 v[56:57], v[56:57], v[144:145], v[186:187]
	v_pk_fma_f32 v[58:59], v[58:59], v[146:147], v[188:189]
	v_add_u32_e32 v190, 0x80000, v156
	global_store_dwordx4 v190, v[60:63], s[4:5]
	global_store_dwordx4 v190, v[56:59], s[4:5] offset:16
	v_add_u32_e32 v157, 0xa0000, v156
	global_load_dwordx4 v[182:185], v157, s[2:3] offset:512
	global_load_dwordx4 v[186:189], v157, s[2:3] offset:528
	s_waitcnt vmcnt(20)
	v_pk_fma_f32 v[52:53], v[52:53], v[140:141], v[198:199]
	v_pk_fma_f32 v[54:55], v[54:55], v[142:143], v[200:201]
	v_pk_fma_f32 v[48:49], v[48:49], v[144:145], v[202:203]
	v_pk_fma_f32 v[50:51], v[50:51], v[146:147], v[204:205]
	v_add_u32_e32 v190, 0x90000, v156
	global_store_dwordx4 v190, v[52:55], s[4:5]
	global_store_dwordx4 v190, v[48:51], s[4:5] offset:16
	v_add_u32_e32 v157, 0xb0000, v156
	global_load_dwordx4 v[198:201], v157, s[2:3] offset:512
	global_load_dwordx4 v[202:205], v157, s[2:3] offset:528
	s_waitcnt vmcnt(20)
	v_pk_fma_f32 v[44:45], v[44:45], v[140:141], v[206:207]
	v_pk_fma_f32 v[46:47], v[46:47], v[142:143], v[208:209]
	v_pk_fma_f32 v[40:41], v[40:41], v[144:145], v[210:211]
	v_pk_fma_f32 v[42:43], v[42:43], v[146:147], v[212:213]
	v_add_u32_e32 v190, 0xa0000, v156
	global_store_dwordx4 v190, v[44:47], s[4:5]
	global_store_dwordx4 v190, v[40:43], s[4:5] offset:16
	s_waitcnt vmcnt(18)
	v_pk_fma_f32 v[36:37], v[36:37], v[140:141], v[214:215]
	v_pk_fma_f32 v[38:39], v[38:39], v[142:143], v[216:217]
	v_pk_fma_f32 v[32:33], v[32:33], v[144:145], v[218:219]
	v_pk_fma_f32 v[34:35], v[34:35], v[146:147], v[220:221]
	v_add_u32_e32 v190, 0xb0000, v156
	global_store_dwordx4 v190, v[36:39], s[4:5]
	global_store_dwordx4 v190, v[32:35], s[4:5] offset:16
	s_waitcnt vmcnt(16)
	v_pk_fma_f32 v[28:29], v[28:29], v[148:149], v[166:167]
	v_pk_fma_f32 v[30:31], v[30:31], v[150:151], v[168:169]
	v_pk_fma_f32 v[24:25], v[24:25], v[152:153], v[170:171]
	v_pk_fma_f32 v[26:27], v[26:27], v[154:155], v[172:173]
	v_add_u32_e32 v190, 0x80000, v156
	global_store_dwordx4 v190, v[28:31], s[4:5] offset:512
	global_store_dwordx4 v190, v[24:27], s[4:5] offset:528
	s_waitcnt vmcnt(14)
	v_pk_fma_f32 v[20:21], v[20:21], v[148:149], v[174:175]
	v_pk_fma_f32 v[22:23], v[22:23], v[150:151], v[176:177]
	v_pk_fma_f32 v[16:17], v[16:17], v[152:153], v[178:179]
	v_pk_fma_f32 v[18:19], v[18:19], v[154:155], v[180:181]
	v_add_u32_e32 v190, 0x90000, v156
	global_store_dwordx4 v190, v[20:23], s[4:5] offset:512
	global_store_dwordx4 v190, v[16:19], s[4:5] offset:528
	s_waitcnt vmcnt(12)
	v_pk_fma_f32 v[12:13], v[12:13], v[148:149], v[182:183]
	v_pk_fma_f32 v[14:15], v[14:15], v[150:151], v[184:185]
	v_pk_fma_f32 v[8:9], v[8:9], v[152:153], v[186:187]
	v_pk_fma_f32 v[10:11], v[10:11], v[154:155], v[188:189]
	v_add_u32_e32 v190, 0xa0000, v156
	global_store_dwordx4 v190, v[12:15], s[4:5] offset:512
	global_store_dwordx4 v190, v[8:11], s[4:5] offset:528
	s_waitcnt vmcnt(10)
	v_pk_fma_f32 v[4:5], v[4:5], v[148:149], v[198:199]
	v_pk_fma_f32 v[6:7], v[6:7], v[150:151], v[200:201]
	v_pk_fma_f32 v[0:1], v[0:1], v[152:153], v[202:203]
	v_pk_fma_f32 v[2:3], v[2:3], v[154:155], v[204:205]
	v_add_u32_e32 v190, 0xb0000, v156
	global_store_dwordx4 v190, v[4:7], s[4:5] offset:512
	global_store_dwordx4 v190, v[0:3], s[4:5] offset:528
	s_mov_b64 s[0:1], -1
	s_and_b64 vcc, s[14:15], exec
	s_cbranch_vccz .LBB0_886
	s_and_b64 vcc, exec, s[6:7]
	s_cbranch_vccz .LBB0_885
	s_barrier
	s_branch .LBB0_885

; __global__ void __launch_bounds__(512) fwd_kernel(Params p) {
;     ...
;                [=](int m, int n, f32x4 v, f32x4 w, int piece) {
;                  float* dst; const float* g;
;                  if (m < NLAT) { dst = p.out + (size_t)m * 1024 + n; g = modl + (size_t)(m >> 11) * 6144 + 5 * 1024 + n; }
;                  else { dst = ((piece == 0) ? ctxs : (cpart + (size_t)(piece - 1) * 2048 * 1024)) + (size_t)(m - NLAT) * 1024 + n; g = modl + (size_t)8 * 6144 + 5 * 1024 + n; }
;                  const float4 g4 = *(const float4*)g; const float4 g5 = *(const float4*)(g + 4);
;                  float4 o; o.x = g4.x * v[0]; o.y = g4.y * v[1]; o.z = g4.z * v[2]; o.w = g4.w * v[3];
;                  float4 o2; o2.x = g5.x * w[0]; o2.y = g5.y * w[1]; o2.z = g5.z * w[2]; o2.w = g5.w * w[3];
;                  if (piece == 0) {
;                    const float4 s4 = *(const float4*)dst; const float4 s5 = *(const float4*)(dst + 4);
;                    o.x += s4.x; o.y += s4.y; o.z += s4.z; o.w += s4.w; o2.x += s5.x; o2.y += s5.y; o2.z += s5.z; o2.w += s5.w;
;                  }
;                  *(float4*)dst = o; *(float4*)(dst + 4) = o2;
;                });
.LBB0_1204:
	s_cmpk_lt_i32 s29, 0x4000
	s_cbranch_scc0 .Lp9e_ctx
	s_mov_b64 s[4:5], s[86:87]
	s_lshr_b32 s1, s29, 11
	s_mul_i32 s1, s1, 0x6000
	s_add_u32 s6, s10, s1
	s_addc_u32 s7, s11, 0
	s_add_u32 s6, s6, 0x5000
	s_addc_u32 s7, s7, 0
	s_mov_b32 s1, s29
	s_branch .Lp9e_join
.Lp9e_ctx:
	s_mov_b64 s[6:7], s[16:17]
	s_add_i32 s1, s29, 0xffffc000
	s_cmp_eq_u32 s28, 0
	s_cbranch_scc0 .Lp9e_part
	v_readlane_b32 s4, v250, 59
	v_readlane_b32 s5, v250, 60
	s_branch .Lp9e_join
.Lp9e_part:
	v_readlane_b32 s4, v250, 61
	v_readlane_b32 s5, v250, 62
	s_add_i32 s2, s28, -1
	s_lshl_b32 s2, s2, 23
	s_nop 1
	s_add_u32 s4, s4, s2
	s_addc_u32 s5, s5, 0
.Lp9e_join:
	s_nop 3
	s_lshl_b32 s2, s0, 2
	s_lshl_b32 s1, s1, 12
	s_add_u32 s1, s1, s2
	s_add_u32 s4, s4, s1
	s_addc_u32 s5, s5, 0
	s_add_u32 s6, s6, s2
	s_addc_u32 s7, s7, 0
	v_lshlrev_b32_e32 v157, 2, v160
	v_lshl_add_u32 v156, v158, 12, v157
	global_load_dwordx4 v[140:143], v157, s[6:7]
	global_load_dwordx4 v[144:147], v157, s[6:7] offset:16
	global_load_dwordx4 v[148:151], v157, s[6:7] offset:512
	global_load_dwordx4 v[152:155], v157, s[6:7] offset:528
	s_cmp_eq_u32 s28, 0
	s_cbranch_scc0 .Lp9e_wo
	global_load_dwordx4 v[166:169], v156, s[4:5]
	global_load_dwordx4 v[170:173], v156, s[4:5] offset:16
	v_add_u32_e32 v157, 0x10000, v156
	global_load_dwordx4 v[174:177], v157, s[4:5]
	global_load_dwordx4 v[178:181], v157, s[4:5] offset:16
	v_add_u32_e32 v157, 0x20000, v156
	global_load_dwordx4 v[182:185], v157, s[4:5]
	global_load_dwordx4 v[186:189], v157, s[4:5] offset:16
	v_add_u32_e32 v157, 0x30000, v156
	global_load_dwordx4 v[198:201], v157, s[4:5]
	global_load_dwordx4 v[202:205], v157, s[4:5] offset:16
	global_load_dwordx4 v[206:209], v156, s[4:5] offset:512
	global_load_dwordx4 v[210:213], v156, s[4:5] offset:528
	v_add_u32_e32 v157, 0x10000, v156
	global_load_dwordx4 v[214:217], v157, s[4:5] offset:512
	global_load_dwordx4 v[218:221], v157, s[4:5] offset:528
	s_waitcnt vmcnt(10)
	v_pk_mul_f32 v[124:125], v[124:125], v[140:141]
	v_pk_mul_f32 v[126:127], v[126:127], v[142:143]
	v_pk_mul_f32 v[120:121], v[120:121], v[144:145]
	v_pk_mul_f32 v[122:123], v[122:123], v[146:147]
	v_pk_add_f32 v[124:125], v[124:125], v[166:167]
	v_pk_add_f32 v[126:127], v[126:127], v[168:169]
	v_pk_add_f32 v[120:121], v[120:121], v[170:171]
	v_pk_add_f32 v[122:123], v[122:123], v[172:173]
	global_store_dwordx4 v156, v[124:127], s[4:5]
	global_store_dwordx4 v156, v[120:123], s[4:5] offset:16
	v_add_u32_e32 v157, 0x20000, v156
	global_load_dwordx4 v[166:169], v157, s[4:5] offset:512
	global_load_dwordx4 v[170:173], v157, s[4:5] offset:528
	s_waitcnt vmcnt(12)
	v_pk_mul_f32 v[116:117], v[116:117], v[140:141]
	v_pk_mul_f32 v[118:119], v[118:119], v[142:143]
	v_pk_mul_f32 v[112:113], v[112:113], v[144:145]
	v_pk_mul_f32 v[114:115], v[114:115], v[146:147]
	v_pk_add_f32 v[116:117], v[116:117], v[174:175]
	v_pk_add_f32 v[118:119], v[118:119], v[176:177]
	v_pk_add_f32 v[112:113], v[112:113], v[178:179]
	v_pk_add_f32 v[114:115], v[114:115], v[180:181]
	v_add_u32_e32 v190, 0x10000, v156
	global_store_dwordx4 v190, v[116:119], s[4:5]
	global_store_dwordx4 v190, v[112:115], s[4:5] offset:16
	v_add_u32_e32 v157, 0x30000, v156
	global_load_dwordx4 v[174:177], v157, s[4:5] offset:512
	global_load_dwordx4 v[178:181], v157, s[4:5] offset:528
	s_waitcnt vmcnt(14)
	v_pk_mul_f32 v[108:109], v[108:109], v[140:141]
	v_pk_mul_f32 v[110:111], v[110:111], v[142:143]
	v_pk_mul_f32 v[104:105], v[104:105], v[144:145]
	v_pk_mul_f32 v[106:107], v[106:107], v[146:147]
	v_pk_add_f32 v[108:109], v[108:109], v[182:183]
	v_pk_add_f32 v[110:111], v[110:111], v[184:185]
	v_pk_add_f32 v[104:105], v[104:105], v[186:187]
	v_pk_add_f32 v[106:107], v[106:107], v[188:189]
	v_add_u32_e32 v190, 0x20000, v156
	global_store_dwordx4 v190, v[108:111], s[4:5]
	global_store_dwordx4 v190, v[104:107], s[4:5] offset:16
	v_add_u32_e32 v157, 0x80000, v156
	global_load_dwordx4 v[182:185], v157, s[4:5]
	global_load_dwordx4 v[186:189], v157, s[4:5] offset:16
	s_waitcnt vmcnt(16)
	v_pk_mul_f32 v[100:101], v[100:101], v[140:141]
	v_pk_mul_f32 v[102:103], v[102:103], v[142:143]
	v_pk_mul_f32 v[96:97], v[96:97], v[144:145]
	v_pk_mul_f32 v[98:99], v[98:99], v[146:147]
	v_pk_add_f32 v[100:101], v[100:101], v[198:199]
	v_pk_add_f32 v[102:103], v[102:103], v[200:201]
	v_pk_add_f32 v[96:97], v[96:97], v[202:203]
	v_pk_add_f32 v[98:99], v[98:99], v[204:205]
	v_add_u32_e32 v190, 0x30000, v156
	global_store_dwordx4 v190, v[100:103], s[4:5]
	global_store_dwordx4 v190, v[96:99], s[4:5] offset:16
	v_add_u32_e32 v157, 0x90000, v156
	global_load_dwordx4 v[198:201], v157, s[4:5]
	global_load_dwordx4 v[202:205], v157, s[4:5] offset:16
	s_waitcnt vmcnt(18)
	v_pk_mul_f32 v[92:93], v[92:93], v[148:149]
	v_pk_mul_f32 v[94:95], v[94:95], v[150:151]
	v_pk_mul_f32 v[88:89], v[88:89], v[152:153]
	v_pk_mul_f32 v[90:91], v[90:91], v[154:155]
	v_pk_add_f32 v[92:93], v[92:93], v[206:207]
	v_pk_add_f32 v[94:95], v[94:95], v[208:209]
	v_pk_add_f32 v[88:89], v[88:89], v[210:211]
	v_pk_add_f32 v[90:91], v[90:91], v[212:213]
	global_store_dwordx4 v156, v[92:95], s[4:5] offset:512
	global_store_dwordx4 v156, v[88:91], s[4:5] offset:528
	v_add_u32_e32 v157, 0xa0000, v156
	global_load_dwordx4 v[206:209], v157, s[4:5]
	global_load_dwordx4 v[210:213], v157, s[4:5] offset:16
	s_waitcnt vmcnt(20)
	v_pk_mul_f32 v[84:85], v[84:85], v[148:149]
	v_pk_mul_f32 v[86:87], v[86:87], v[150:151]
	v_pk_mul_f32 v[80:81], v[80:81], v[152:153]
	v_pk_mul_f32 v[82:83], v[82:83], v[154:155]
	v_pk_add_f32 v[84:85], v[84:85], v[214:215]
	v_pk_add_f32 v[86:87], v[86:87], v[216:217]
	v_pk_add_f32 v[80:81], v[80:81], v[218:219]
	v_pk_add_f32 v[82:83], v[82:83], v[220:221]
	v_add_u32_e32 v190, 0x10000, v156
	global_store_dwordx4 v190, v[84:87], s[4:5] offset:512
	global_store_dwordx4 v190, v[80:83], s[4:5] offset:528
	v_add_u32_e32 v157, 0xb0000, v156
	global_load_dwordx4 v[214:217], v157, s[4:5]
	global_load_dwordx4 v[218:221], v157, s[4:5] offset:16
	s_waitcnt vmcnt(20)
; __global__ void __launch_bounds__(512) fwd_kernel(Params p) {
;     ...
;                [=](int m, int n, f32x4 v, f32x4 w, int piece) {
;                  float* dst; const float* g;
;                  if (m < NLAT) { dst = p.out + (size_t)m * 1024 + n; g = modl + (size_t)(m >> 11) * 6144 + 5 * 1024 + n; }
;                  else { dst = ((piece == 0) ? ctxs : (cpart + (size_t)(piece - 1) * 2048 * 1024)) + (size_t)(m - NLAT) * 1024 + n; g = modl + (size_t)8 * 6144 + 5 * 1024 + n; }
;                  const float4 g4 = *(const float4*)g; const float4 g5 = *(const float4*)(g + 4);
;                  float4 o; o.x = g4.x * v[0]; o.y = g4.y * v[1]; o.z = g4.z * v[2]; o.w = g4.w * v[3];
;                  float4 o2; o2.x = g5.x * w[0]; o2.y = g5.y * w[1]; o2.z = g5.z * w[2]; o2.w = g5.w * w[3];
;                  if (piece == 0) {
;                    const float4 s4 = *(const float4*)dst; const float4 s5 = *(const float4*)(dst + 4);
;                    o.x += s4.x; o.y += s4.y; o.z += s4.z; o.w += s4.w; o2.x += s5.x; o2.y += s5.y; o2.z += s5.z; o2.w += s5.w;
;                  }
;                  *(float4*)dst = o; *(float4*)(dst + 4) = o2;
;                });
	v_pk_mul_f32 v[76:77], v[76:77], v[148:149]
	v_pk_mul_f32 v[78:79], v[78:79], v[150:151]
	v_pk_mul_f32 v[72:73], v[72:73], v[152:153]
	v_pk_mul_f32 v[74:75], v[74:75], v[154:155]
	v_pk_add_f32 v[76:77], v[76:77], v[166:167]
	v_pk_add_f32 v[78:79], v[78:79], v[168:169]
	v_pk_add_f32 v[72:73], v[72:73], v[170:171]
	v_pk_add_f32 v[74:75], v[74:75], v[172:173]
	v_add_u32_e32 v190, 0x20000, v156
	global_store_dwordx4 v190, v[76:79], s[4:5] offset:512
	global_store_dwordx4 v190, v[72:75], s[4:5] offset:528
	v_add_u32_e32 v157, 0x80000, v156
	global_load_dwordx4 v[166:169], v157, s[4:5] offset:512
	global_load_dwordx4 v[170:173], v157, s[4:5] offset:528
	s_waitcnt vmcnt(20)
	v_pk_mul_f32 v[68:69], v[68:69], v[148:149]
	v_pk_mul_f32 v[70:71], v[70:71], v[150:151]
	v_pk_mul_f32 v[64:65], v[64:65], v[152:153]
	v_pk_mul_f32 v[66:67], v[66:67], v[154:155]
	v_pk_add_f32 v[68:69], v[68:69], v[174:175]
	v_pk_add_f32 v[70:71], v[70:71], v[176:177]
	v_pk_add_f32 v[64:65], v[64:65], v[178:179]
	v_pk_add_f32 v[66:67], v[66:67], v[180:181]
	v_add_u32_e32 v190, 0x30000, v156
	global_store_dwordx4 v190, v[68:71], s[4:5] offset:512
	global_store_dwordx4 v190, v[64:67], s[4:5] offset:528
	v_add_u32_e32 v157, 0x90000, v156
	global_load_dwordx4 v[174:177], v157, s[4:5] offset:512
	global_load_dwordx4 v[178:181], v157, s[4:5] offset:528
	s_waitcnt vmcnt(20)
	v_pk_mul_f32 v[60:61], v[60:61], v[140:141]
	v_pk_mul_f32 v[62:63], v[62:63], v[142:143]
	v_pk_mul_f32 v[56:57], v[56:57], v[144:145]
	v_pk_mul_f32 v[58:59], v[58:59], v[146:147]
	v_pk_add_f32 v[60:61], v[60:61], v[182:183]
	v_pk_add_f32 v[62:63], v[62:63], v[184:185]
	v_pk_add_f32 v[56:57], v[56:57], v[186:187]
	v_pk_add_f32 v[58:59], v[58:59], v[188:189]
	v_add_u32_e32 v190, 0x80000, v156
	global_store_dwordx4 v190, v[60:63], s[4:5]
	global_store_dwordx4 v190, v[56:59], s[4:5] offset:16
	v_add_u32_e32 v157, 0xa0000, v156
	global_load_dwordx4 v[182:185], v157, s[4:5] offset:512
	global_load_dwordx4 v[186:189], v157, s[4:5] offset:528
	s_waitcnt vmcnt(20)
	v_pk_mul_f32 v[52:53], v[52:53], v[140:141]
	v_pk_mul_f32 v[54:55], v[54:55], v[142:143]
	v_pk_mul_f32 v[48:49], v[48:49], v[144:145]
	v_pk_mul_f32 v[50:51], v[50:51], v[146:147]
	v_pk_add_f32 v[52:53], v[52:53], v[198:199]
	v_pk_add_f32 v[54:55], v[54:55], v[200:201]
	v_pk_add_f32 v[48:49], v[48:49], v[202:203]
	v_pk_add_f32 v[50:51], v[50:51], v[204:205]
	v_add_u32_e32 v190, 0x90000, v156
	global_store_dwordx4 v190, v[52:55], s[4:5]
	global_store_dwordx4 v190, v[48:51], s[4:5] offset:16
	v_add_u32_e32 v157, 0xb0000, v156
	global_load_dwordx4 v[198:201], v157, s[4:5] offset:512
	global_load_dwordx4 v[202:205], v157, s[4:5] offset:528
	s_waitcnt vmcnt(20)
	v_pk_mul_f32 v[44:45], v[44:45], v[140:141]
	v_pk_mul_f32 v[46:47], v[46:47], v[142:143]
	v_pk_mul_f32 v[40:41], v[40:41], v[144:145]
	v_pk_mul_f32 v[42:43], v[42:43], v[146:147]
	v_pk_add_f32 v[44:45], v[44:45], v[206:207]
	v_pk_add_f32 v[46:47], v[46:47], v[208:209]
	v_pk_add_f32 v[40:41], v[40:41], v[210:211]
	v_pk_add_f32 v[42:43], v[42:43], v[212:213]
	v_add_u32_e32 v190, 0xa0000, v156
	global_store_dwordx4 v190, v[44:47], s[4:5]
	global_store_dwordx4 v190, v[40:43], s[4:5] offset:16
	s_waitcnt vmcnt(18)
	v_pk_mul_f32 v[36:37], v[36:37], v[140:141]
	v_pk_mul_f32 v[38:39], v[38:39], v[142:143]
	v_pk_mul_f32 v[32:33], v[32:33], v[144:145]
	v_pk_mul_f32 v[34:35], v[34:35], v[146:147]
	v_pk_add_f32 v[36:37], v[36:37], v[214:215]
	v_pk_add_f32 v[38:39], v[38:39], v[216:217]
	v_pk_add_f32 v[32:33], v[32:33], v[218:219]
	v_pk_add_f32 v[34:35], v[34:35], v[220:221]
	v_add_u32_e32 v190, 0xb0000, v156
	global_store_dwordx4 v190, v[36:39], s[4:5]
	global_store_dwordx4 v190, v[32:35], s[4:5] offset:16
	s_waitcnt vmcnt(16)
	v_pk_mul_f32 v[28:29], v[28:29], v[148:149]
	v_pk_mul_f32 v[30:31], v[30:31], v[150:151]
	v_pk_mul_f32 v[24:25], v[24:25], v[152:153]
	v_pk_mul_f32 v[26:27], v[26:27], v[154:155]
	v_pk_add_f32 v[28:29], v[28:29], v[166:167]
	v_pk_add_f32 v[30:31], v[30:31], v[168:169]
	v_pk_add_f32 v[24:25], v[24:25], v[170:171]
	v_pk_add_f32 v[26:27], v[26:27], v[172:173]
	v_add_u32_e32 v190, 0x80000, v156
	global_store_dwordx4 v190, v[28:31], s[4:5] offset:512
	global_store_dwordx4 v190, v[24:27], s[4:5] offset:528
	s_waitcnt vmcnt(14)
	v_pk_mul_f32 v[20:21], v[20:21], v[148:149]
	v_pk_mul_f32 v[22:23], v[22:23], v[150:151]
	v_pk_mul_f32 v[16:17], v[16:17], v[152:153]
	v_pk_mul_f32 v[18:19], v[18:19], v[154:155]
	v_pk_add_f32 v[20:21], v[20:21], v[174:175]
	v_pk_add_f32 v[22:23], v[22:23], v[176:177]
	v_pk_add_f32 v[16:17], v[16:17], v[178:179]
	v_pk_add_f32 v[18:19], v[18:19], v[180:181]
	v_add_u32_e32 v190, 0x90000, v156
	global_store_dwordx4 v190, v[20:23], s[4:5] offset:512
	global_store_dwordx4 v190, v[16:19], s[4:5] offset:528
	s_waitcnt vmcnt(12)
	v_pk_mul_f32 v[12:13], v[12:13], v[148:149]
	v_pk_mul_f32 v[14:15], v[14:15], v[150:151]
	v_pk_mul_f32 v[8:9], v[8:9], v[152:153]
	v_pk_mul_f32 v[10:11], v[10:11], v[154:155]
	v_pk_add_f32 v[12:13], v[12:13], v[182:183]
	v_pk_add_f32 v[14:15], v[14:15], v[184:185]
	v_pk_add_f32 v[8:9], v[8:9], v[186:187]
	v_pk_add_f32 v[10:11], v[10:11], v[188:189]
	v_add_u32_e32 v190, 0xa0000, v156
	global_store_dwordx4 v190, v[12:15], s[4:5] offset:512
	global_store_dwordx4 v190, v[8:11], s[4:5] offset:528
	s_waitcnt vmcnt(10)
	v_pk_mul_f32 v[4:5], v[4:5], v[148:149]
	v_pk_mul_f32 v[6:7], v[6:7], v[150:151]
	v_pk_mul_f32 v[0:1], v[0:1], v[152:153]
	v_pk_mul_f32 v[2:3], v[2:3], v[154:155]
	v_pk_add_f32 v[4:5], v[4:5], v[198:199]
	v_pk_add_f32 v[6:7], v[6:7], v[200:201]
	v_pk_add_f32 v[0:1], v[0:1], v[202:203]
	v_pk_add_f32 v[2:3], v[2:3], v[204:205]
	v_add_u32_e32 v190, 0xb0000, v156
	global_store_dwordx4 v190, v[4:7], s[4:5] offset:512
	global_store_dwordx4 v190, v[0:3], s[4:5] offset:528
	s_branch .Lp9e_done
; #define PG8_BAR __builtin_amdgcn_s_barrier()
; template <class Epi>
; __device__ __forceinline__ void gemm_phase(unsigned char* lds_g, const bf16_t* A0, const bf16_t* A1, int lda, const bf16_t* Bt, int K,
;                            int mtiles, int ntiles, int ksplit, Epi epi) {
;     ...
;       if (!has_next) break;
; #pragma unroll
;       for (int a = 0; a < 2; ++a)
; #pragma unroll
;         for (int b = 0; b < 2; ++b)
; #pragma unroll
;           for (int m = 0; m < 4; ++m)
; #pragma unroll
;             for (int n = 0; n < 2; ++n) acc[a][b][m][n] = (f32x4){0.f, 0.f, 0.f, 0.f};
;       cur = nxt; cA = nA; cB = nB; ++ui;
;       if (G_ALIGN) { if (wr == 1) PG8_BAR; }
; __global__ void __launch_bounds__(512) fwd_kernel(Params p) {
;     ...
;                [=](int m, int n, f32x4 v, f32x4 w, int piece) {
;                  float* dst; const float* g;
;                  if (m < NLAT) { dst = p.out + (size_t)m * 1024 + n; g = modl + (size_t)(m >> 11) * 6144 + 5 * 1024 + n; }
;                  else { dst = ((piece == 0) ? ctxs : (cpart + (size_t)(piece - 1) * 2048 * 1024)) + (size_t)(m - NLAT) * 1024 + n; g = modl + (size_t)8 * 6144 + 5 * 1024 + n; }
;                  const float4 g4 = *(const float4*)g; const float4 g5 = *(const float4*)(g + 4);
;                  float4 o; o.x = g4.x * v[0]; o.y = g4.y * v[1]; o.z = g4.z * v[2]; o.w = g4.w * v[3];
;                  float4 o2; o2.x = g5.x * w[0]; o2.y = g5.y * w[1]; o2.z = g5.z * w[2]; o2.w = g5.w * w[3];
;                  if (piece == 0) {
;                    const float4 s4 = *(const float4*)dst; const float4 s5 = *(const float4*)(dst + 4);
;                    o.x += s4.x; o.y += s4.y; o.z += s4.z; o.w += s4.w; o2.x += s5.x; o2.y += s5.y; o2.z += s5.z; o2.w += s5.w;
;                  }
;                  *(float4*)dst = o; *(float4*)(dst + 4) = o2;
;                });
.Lp9e_wo:
	s_waitcnt vmcnt(0)
	v_pk_mul_f32 v[124:125], v[124:125], v[140:141]
	v_pk_mul_f32 v[126:127], v[126:127], v[142:143]
	v_pk_mul_f32 v[120:121], v[120:121], v[144:145]
	v_pk_mul_f32 v[122:123], v[122:123], v[146:147]
	global_store_dwordx4 v156, v[124:127], s[4:5]
	global_store_dwordx4 v156, v[120:123], s[4:5] offset:16
	v_pk_mul_f32 v[116:117], v[116:117], v[140:141]
	v_pk_mul_f32 v[118:119], v[118:119], v[142:143]
	v_pk_mul_f32 v[112:113], v[112:113], v[144:145]
	v_pk_mul_f32 v[114:115], v[114:115], v[146:147]
	v_add_u32_e32 v190, 0x10000, v156
	global_store_dwordx4 v190, v[116:119], s[4:5]
	global_store_dwordx4 v190, v[112:115], s[4:5] offset:16
	v_pk_mul_f32 v[108:109], v[108:109], v[140:141]
	v_pk_mul_f32 v[110:111], v[110:111], v[142:143]
	v_pk_mul_f32 v[104:105], v[104:105], v[144:145]
	v_pk_mul_f32 v[106:107], v[106:107], v[146:147]
	v_add_u32_e32 v190, 0x20000, v156
	global_store_dwordx4 v190, v[108:111], s[4:5]
	global_store_dwordx4 v190, v[104:107], s[4:5] offset:16
	v_pk_mul_f32 v[100:101], v[100:101], v[140:141]
	v_pk_mul_f32 v[102:103], v[102:103], v[142:143]
	v_pk_mul_f32 v[96:97], v[96:97], v[144:145]
	v_pk_mul_f32 v[98:99], v[98:99], v[146:147]
	v_add_u32_e32 v190, 0x30000, v156
	global_store_dwordx4 v190, v[100:103], s[4:5]
	global_store_dwordx4 v190, v[96:99], s[4:5] offset:16
	v_pk_mul_f32 v[92:93], v[92:93], v[148:149]
	v_pk_mul_f32 v[94:95], v[94:95], v[150:151]
	v_pk_mul_f32 v[88:89], v[88:89], v[152:153]
	v_pk_mul_f32 v[90:91], v[90:91], v[154:155]
	global_store_dwordx4 v156, v[92:95], s[4:5] offset:512
	global_store_dwordx4 v156, v[88:91], s[4:5] offset:528
	v_pk_mul_f32 v[84:85], v[84:85], v[148:149]
	v_pk_mul_f32 v[86:87], v[86:87], v[150:151]
	v_pk_mul_f32 v[80:81], v[80:81], v[152:153]
	v_pk_mul_f32 v[82:83], v[82:83], v[154:155]
	v_add_u32_e32 v190, 0x10000, v156
	global_store_dwordx4 v190, v[84:87], s[4:5] offset:512
	global_store_dwordx4 v190, v[80:83], s[4:5] offset:528
	v_pk_mul_f32 v[76:77], v[76:77], v[148:149]
	v_pk_mul_f32 v[78:79], v[78:79], v[150:151]
	v_pk_mul_f32 v[72:73], v[72:73], v[152:153]
	v_pk_mul_f32 v[74:75], v[74:75], v[154:155]
	v_add_u32_e32 v190, 0x20000, v156
	global_store_dwordx4 v190, v[76:79], s[4:5] offset:512
	global_store_dwordx4 v190, v[72:75], s[4:5] offset:528
	v_pk_mul_f32 v[68:69], v[68:69], v[148:149]
	v_pk_mul_f32 v[70:71], v[70:71], v[150:151]
	v_pk_mul_f32 v[64:65], v[64:65], v[152:153]
	v_pk_mul_f32 v[66:67], v[66:67], v[154:155]
	v_add_u32_e32 v190, 0x30000, v156
	global_store_dwordx4 v190, v[68:71], s[4:5] offset:512
	global_store_dwordx4 v190, v[64:67], s[4:5] offset:528
	v_pk_mul_f32 v[60:61], v[60:61], v[140:141]
	v_pk_mul_f32 v[62:63], v[62:63], v[142:143]
	v_pk_mul_f32 v[56:57], v[56:57], v[144:145]
	v_pk_mul_f32 v[58:59], v[58:59], v[146:147]
	v_add_u32_e32 v190, 0x80000, v156
	global_store_dwordx4 v190, v[60:63], s[4:5]
	global_store_dwordx4 v190, v[56:59], s[4:5] offset:16
	v_pk_mul_f32 v[52:53], v[52:53], v[140:141]
	v_pk_mul_f32 v[54:55], v[54:55], v[142:143]
	v_pk_mul_f32 v[48:49], v[48:49], v[144:145]
	v_pk_mul_f32 v[50:51], v[50:51], v[146:147]
	v_add_u32_e32 v190, 0x90000, v156
	global_store_dwordx4 v190, v[52:55], s[4:5]
	global_store_dwordx4 v190, v[48:51], s[4:5] offset:16
	v_pk_mul_f32 v[44:45], v[44:45], v[140:141]
	v_pk_mul_f32 v[46:47], v[46:47], v[142:143]
	v_pk_mul_f32 v[40:41], v[40:41], v[144:145]
	v_pk_mul_f32 v[42:43], v[42:43], v[146:147]
	v_add_u32_e32 v190, 0xa0000, v156
	global_store_dwordx4 v190, v[44:47], s[4:5]
	global_store_dwordx4 v190, v[40:43], s[4:5] offset:16
	v_pk_mul_f32 v[36:37], v[36:37], v[140:141]
	v_pk_mul_f32 v[38:39], v[38:39], v[142:143]
	v_pk_mul_f32 v[32:33], v[32:33], v[144:145]
	v_pk_mul_f32 v[34:35], v[34:35], v[146:147]
	v_add_u32_e32 v190, 0xb0000, v156
	global_store_dwordx4 v190, v[36:39], s[4:5]
	global_store_dwordx4 v190, v[32:35], s[4:5] offset:16
	v_pk_mul_f32 v[28:29], v[28:29], v[148:149]
	v_pk_mul_f32 v[30:31], v[30:31], v[150:151]
	v_pk_mul_f32 v[24:25], v[24:25], v[152:153]
	v_pk_mul_f32 v[26:27], v[26:27], v[154:155]
	v_add_u32_e32 v190, 0x80000, v156
	global_store_dwordx4 v190, v[28:31], s[4:5] offset:512
	global_store_dwordx4 v190, v[24:27], s[4:5] offset:528
	v_pk_mul_f32 v[20:21], v[20:21], v[148:149]
	v_pk_mul_f32 v[22:23], v[22:23], v[150:151]
	v_pk_mul_f32 v[16:17], v[16:17], v[152:153]
	v_pk_mul_f32 v[18:19], v[18:19], v[154:155]
	v_add_u32_e32 v190, 0x90000, v156
	global_store_dwordx4 v190, v[20:23], s[4:5] offset:512
	global_store_dwordx4 v190, v[16:19], s[4:5] offset:528
	v_pk_mul_f32 v[12:13], v[12:13], v[148:149]
	v_pk_mul_f32 v[14:15], v[14:15], v[150:151]
	v_pk_mul_f32 v[8:9], v[8:9], v[152:153]
	v_pk_mul_f32 v[10:11], v[10:11], v[154:155]
	v_add_u32_e32 v190, 0xa0000, v156
	global_store_dwordx4 v190, v[12:15], s[4:5] offset:512
	global_store_dwordx4 v190, v[8:11], s[4:5] offset:528
	v_pk_mul_f32 v[4:5], v[4:5], v[148:149]
	v_pk_mul_f32 v[6:7], v[6:7], v[150:151]
	v_pk_mul_f32 v[0:1], v[0:1], v[152:153]
	v_pk_mul_f32 v[2:3], v[2:3], v[154:155]
	v_add_u32_e32 v190, 0xb0000, v156
	global_store_dwordx4 v190, v[4:7], s[4:5] offset:512
	global_store_dwordx4 v190, v[0:3], s[4:5] offset:528
.Lp9e_done:
	s_mov_b64 s[0:1], -1
	s_and_b64 vcc, exec, s[22:23]
	s_cbranch_vccz .LBB0_1192
	s_and_b64 vcc, exec, s[12:13]
	s_cbranch_vccz .LBB0_1191
	s_barrier
	s_branch .LBB0_1191
